# phase0 row sum-of-squares reduction: 6 ds_bpermute hops replaced by permlane32/16_swap + DPP row_ror/quad_perm (same pairing, bit-identical)
# baseline (speedup 1.0000x reference)
.LBB0_87:
	s_andn2_b64 vcc, exec, s[12:13]
	s_cbranch_vccnz .LBB0_10
	v_lshl_add_u32 v80, s19, 5, v103
	v_lshlrev_b32_e32 v66, 10, v80
	v_lshl_add_u64 v[2:3], v[66:67], 2, v[72:73]
	global_load_dwordx4 v[46:49], v[2:3], off nt
	global_load_dwordx4 v[42:45], v[2:3], off offset:1024 nt
	global_load_dwordx4 v[38:41], v[2:3], off offset:2048 nt
	global_load_dwordx4 v[34:37], v[2:3], off offset:3072 nt
	v_mov_b32_e32 v3, v67
	v_mov_b32_e32 v85, v67
	v_or_b32_e32 v2, 0x400, v66
	v_or_b32_e32 v84, 0x800, v66
	v_mov_b32_e32 v83, v67
	v_or_b32_e32 v82, 0xc00, v66
	v_lshl_add_u64 v[2:3], v[2:3], 2, v[72:73]
	v_lshl_add_u64 v[4:5], v[84:85], 2, v[72:73]
	v_lshl_add_u64 v[120:121], v[82:83], 2, v[72:73]
	global_load_dwordx4 v[62:65], v[2:3], off nt
	global_load_dwordx4 v[54:57], v[2:3], off offset:1024 nt
	global_load_dwordx4 v[58:61], v[2:3], off offset:2048 nt
	global_load_dwordx4 v[50:53], v[2:3], off offset:3072 nt
	global_load_dwordx4 v[30:33], v[4:5], off nt
	s_waitcnt lgkmcnt(0)
	global_load_dwordx4 v[22:25], v[4:5], off offset:1024 nt
	global_load_dwordx4 v[26:29], v[4:5], off offset:2048 nt
	global_load_dwordx4 v[18:21], v[4:5], off offset:3072 nt
	global_load_dwordx4 v[14:17], v[120:121], off nt
	global_load_dwordx4 v[10:13], v[120:121], off offset:1024 nt
	global_load_dwordx4 v[6:9], v[120:121], off offset:2048 nt
	s_nop 0
	global_load_dwordx4 v[2:5], v[120:121], off offset:3072 nt
	v_and_b32_e32 v81, 64, v119
	v_xor_b32_e32 v83, 32, v119
	v_add_u32_e32 v81, 64, v81
	v_cmp_lt_i32_e32 vcc, v83, v81
	s_waitcnt vmcnt(15)
	v_mul_f32_e32 v85, v47, v47
	s_waitcnt vmcnt(14)
	v_mul_f32_e32 v120, v43, v43
	s_waitcnt vmcnt(13)
	v_mul_f32_e32 v121, v39, v39
	v_fmac_f32_e32 v85, v46, v46
	v_fmac_f32_e32 v120, v42, v42
	s_waitcnt vmcnt(12)
	v_mul_f32_e32 v122, v35, v35
	v_fmac_f32_e32 v121, v38, v38
	v_fmac_f32_e32 v85, v48, v48
	v_fmac_f32_e32 v120, v44, v44
	v_fmac_f32_e32 v122, v34, v34
	v_fmac_f32_e32 v121, v40, v40
	v_fmac_f32_e32 v85, v49, v49
	v_fmac_f32_e32 v120, v45, v45
	v_fmac_f32_e32 v122, v36, v36
	v_fmac_f32_e32 v121, v41, v41
	v_add_f32_e32 v85, v85, v120
	v_cndmask_b32_e32 v83, v119, v83, vcc
	v_fmac_f32_e32 v122, v37, v37
	v_add_f32_e32 v85, v85, v121
	v_lshlrev_b32_e32 v83, 2, v83
	v_add_f32_e32 v120, v85, v122
	v_mov_b32_e32 v121, v120
	v_mov_b32_e32 v127, v120
	s_nop 1
	v_permlane32_swap_b32_e32 v121, v127
	v_xor_b32_e32 v85, 16, v119
	v_cmp_lt_i32_e32 vcc, v85, v81
	s_waitcnt lgkmcnt(0)
	v_add_f32_e32 v121, v121, v127
	v_cndmask_b32_e32 v85, v119, v85, vcc
	v_lshlrev_b32_e32 v85, 2, v85
	v_mov_b32_e32 v122, v121
	v_mov_b32_e32 v127, v121
	s_nop 1
	v_permlane16_swap_b32_e32 v122, v127
	v_xor_b32_e32 v120, 8, v119
	v_cmp_lt_i32_e32 vcc, v120, v81
	s_waitcnt lgkmcnt(0)
	v_add_f32_e32 v122, v122, v127
	v_cndmask_b32_e32 v120, v119, v120, vcc
	v_lshlrev_b32_e32 v120, 2, v120
	s_nop 1
	v_mov_b32_dpp v123, v122 row_ror:8 row_mask:0xf bank_mask:0xf
	v_xor_b32_e32 v121, 4, v119
	v_cmp_lt_i32_e32 vcc, v121, v81
	s_waitcnt lgkmcnt(0)
	v_add_f32_e32 v123, v122, v123
	v_cndmask_b32_e32 v121, v119, v121, vcc
	v_lshlrev_b32_e32 v121, 2, v121
	s_nop 1
	v_mov_b32_dpp v124, v123 row_shl:4 row_mask:0xf bank_mask:0x5
	v_mov_b32_dpp v124, v123 row_shr:4 row_mask:0xf bank_mask:0xa
	v_xor_b32_e32 v122, 2, v119
	v_cmp_lt_i32_e32 vcc, v122, v81
	s_waitcnt lgkmcnt(0)
	v_add_f32_e32 v124, v123, v124
	v_cndmask_b32_e32 v122, v119, v122, vcc
	v_lshlrev_b32_e32 v122, 2, v122
	s_nop 1
	v_mov_b32_dpp v125, v124 quad_perm:[2,3,0,1] row_mask:0xf bank_mask:0xf
	v_xor_b32_e32 v123, 1, v119
	v_cmp_lt_i32_e32 vcc, v123, v81
	s_nop 1
	v_cndmask_b32_e32 v81, v119, v123, vcc
	v_lshlrev_b32_e32 v123, 2, v81
	s_waitcnt lgkmcnt(0)
	v_add_f32_e32 v81, v124, v125
	s_nop 1
	v_mov_b32_dpp v124, v81 quad_perm:[1,0,3,2] row_mask:0xf bank_mask:0xf
	s_and_saveexec_b64 s[12:13], s[4:5]
	s_cbranch_execz .LBB0_90
	s_waitcnt lgkmcnt(0)
	v_add_f32_e32 v81, v81, v124
	v_fmamk_f32 v81, v81, 0x3a800000, v115
	v_mul_f32_e32 v124, 0x4b800000, v81
	v_cmp_gt_f32_e32 vcc, s23, v81
	s_nop 1
	v_cndmask_b32_e32 v81, v81, v124, vcc
	v_rsq_f32_e32 v124, v81
	v_mov_b32_e32 v81, v67
	v_mul_f32_e32 v125, 0x45800000, v124
	v_cndmask_b32_e32 v126, v124, v125, vcc
	v_lshl_add_u64 v[124:125], v[80:81], 2, s[72:73]
	global_store_dword v[124:125], v126, off
.LBB0_90:
	s_or_b64 exec, exec, s[12:13]
	s_waitcnt vmcnt(11)
	v_mul_f32_e32 v81, v63, v63
	s_waitcnt vmcnt(10) lgkmcnt(0)
	v_mul_f32_e32 v124, v55, v55
	v_fmac_f32_e32 v81, v62, v62
	v_fmac_f32_e32 v124, v54, v54
	v_fmac_f32_e32 v81, v64, v64
	v_fmac_f32_e32 v124, v56, v56
	v_fmac_f32_e32 v81, v65, v65
	v_fmac_f32_e32 v124, v57, v57
	v_add_f32_e32 v81, v81, v124
	s_waitcnt vmcnt(9)
	v_mul_f32_e32 v124, v59, v59
	v_fmac_f32_e32 v124, v58, v58
	v_fmac_f32_e32 v124, v60, v60
	v_fmac_f32_e32 v124, v61, v61
	v_add_f32_e32 v81, v81, v124
	s_waitcnt vmcnt(8)
	v_mul_f32_e32 v124, v51, v51
	v_fmac_f32_e32 v124, v50, v50
	v_fmac_f32_e32 v124, v52, v52
	v_fmac_f32_e32 v124, v53, v53
	v_add_f32_e32 v81, v81, v124
	v_mov_b32_e32 v124, v81
	v_mov_b32_e32 v127, v81
	s_nop 1
	v_permlane32_swap_b32_e32 v124, v127
	v_cvt_pk_bf16_f32 v125, v48, v49
	v_lshlrev_b32_e32 v66, 1, v66
	v_cvt_pk_bf16_f32 v42, v42, v43
	v_cvt_pk_bf16_f32 v43, v44, v45
	s_waitcnt lgkmcnt(0)
	v_add_f32_e32 v81, v124, v127
	v_mov_b32_e32 v124, v81
	v_mov_b32_e32 v127, v81
	s_nop 1
	v_permlane16_swap_b32_e32 v124, v127
	v_cvt_pk_bf16_f32 v34, v34, v35
	v_cvt_pk_bf16_f32 v35, v36, v37
	s_waitcnt lgkmcnt(0)
	v_add_f32_e32 v81, v124, v127
	s_nop 1
	v_mov_b32_dpp v126, v81 row_ror:8 row_mask:0xf bank_mask:0xf
	v_cvt_pk_bf16_f32 v124, v46, v47
	v_lshl_add_u64 v[46:47], v[74:75], 0, v[66:67]
	global_store_dwordx2 v[46:47], v[42:43], off offset:512
	v_cvt_pk_bf16_f32 v42, v38, v39
	s_waitcnt lgkmcnt(0)
	v_add_f32_e32 v48, v81, v126
	s_nop 1
	v_mov_b32_dpp v49, v48 row_shl:4 row_mask:0xf bank_mask:0x5
	v_mov_b32_dpp v49, v48 row_shr:4 row_mask:0xf bank_mask:0xa
	v_cvt_pk_bf16_f32 v43, v40, v41
	global_store_dwordx2 v[46:47], v[124:125], off
	global_store_dwordx2 v[46:47], v[42:43], off offset:1024
	global_store_dwordx2 v[46:47], v[34:35], off offset:1536
	s_waitcnt lgkmcnt(0)
	v_add_f32_e32 v48, v48, v49
	s_nop 1
	v_mov_b32_dpp v49, v48 quad_perm:[2,3,0,1] row_mask:0xf bank_mask:0xf
	s_waitcnt lgkmcnt(0)
	v_add_f32_e32 v38, v48, v49
	s_nop 1
	v_mov_b32_dpp v39, v38 quad_perm:[1,0,3,2] row_mask:0xf bank_mask:0xf
	s_and_saveexec_b64 s[12:13], s[4:5]
	s_cbranch_execz .LBB0_92
	s_waitcnt lgkmcnt(0)
	v_add_f32_e32 v34, v38, v39
	v_fmamk_f32 v34, v34, 0x3a800000, v115
	v_mul_f32_e32 v35, 0x4b800000, v34
	v_cmp_gt_f32_e32 vcc, s23, v34
	v_mov_b32_e32 v81, v67
	s_nop 0
	v_cndmask_b32_e32 v34, v34, v35, vcc
	v_rsq_f32_e32 v34, v34
	s_nop 0
	v_mul_f32_e32 v35, 0x45800000, v34
	v_cndmask_b32_e32 v36, v34, v35, vcc
	v_lshl_add_u64 v[34:35], v[80:81], 2, s[72:73]
	global_store_dword v[34:35], v36, off offset:4
.LBB0_92:
	s_or_b64 exec, exec, s[12:13]
	s_waitcnt vmcnt(11)
	v_mul_f32_e32 v34, v31, v31
	s_waitcnt vmcnt(10)
	v_mul_f32_e32 v35, v23, v23
	v_fmac_f32_e32 v34, v30, v30
	v_fmac_f32_e32 v35, v22, v22
	v_fmac_f32_e32 v34, v32, v32
	v_fmac_f32_e32 v35, v24, v24
	v_fmac_f32_e32 v34, v33, v33
	v_fmac_f32_e32 v35, v25, v25
	v_add_f32_e32 v34, v34, v35
	s_waitcnt vmcnt(9)
	v_mul_f32_e32 v35, v27, v27
	v_fmac_f32_e32 v35, v26, v26
	v_fmac_f32_e32 v35, v28, v28
	v_fmac_f32_e32 v35, v29, v29
	v_add_f32_e32 v34, v34, v35
	s_waitcnt vmcnt(8)
	v_mul_f32_e32 v35, v19, v19
	v_fmac_f32_e32 v35, v18, v18
	v_fmac_f32_e32 v35, v20, v20
	v_fmac_f32_e32 v35, v21, v21
	v_add_f32_e32 v34, v34, v35
	v_mov_b32_e32 v35, v34
	v_mov_b32_e32 v127, v34
	s_nop 1
	v_permlane32_swap_b32_e32 v35, v127
	s_waitcnt lgkmcnt(0)
	v_add_f32_e32 v34, v35, v127
	v_mov_b32_e32 v35, v34
	v_mov_b32_e32 v127, v34
	s_nop 1
	v_permlane16_swap_b32_e32 v35, v127
	s_waitcnt lgkmcnt(0)
	v_add_f32_e32 v34, v35, v127
	s_nop 1
	v_mov_b32_dpp v35, v34 row_ror:8 row_mask:0xf bank_mask:0xf
	s_waitcnt lgkmcnt(0)
	v_add_f32_e32 v36, v34, v35
	s_nop 1
	v_mov_b32_dpp v37, v36 row_shl:4 row_mask:0xf bank_mask:0x5
	v_mov_b32_dpp v37, v36 row_shr:4 row_mask:0xf bank_mask:0xa
	v_cvt_pk_bf16_f32 v34, v62, v63
	v_cvt_pk_bf16_f32 v35, v64, v65
	global_store_dwordx2 v[46:47], v[34:35], off offset:2048
	v_cvt_pk_bf16_f32 v34, v54, v55
	s_waitcnt lgkmcnt(0)
	v_add_f32_e32 v38, v36, v37
	s_nop 1
	v_mov_b32_dpp v39, v38 quad_perm:[2,3,0,1] row_mask:0xf bank_mask:0xf
	v_cvt_pk_bf16_f32 v35, v56, v57
	global_store_dwordx2 v[46:47], v[34:35], off offset:2560
	v_cvt_pk_bf16_f32 v36, v58, v59
	v_cvt_pk_bf16_f32 v37, v60, v61
	s_waitcnt lgkmcnt(0)
	v_add_f32_e32 v34, v38, v39
	s_nop 1
	v_mov_b32_dpp v35, v34 quad_perm:[1,0,3,2] row_mask:0xf bank_mask:0xf
	global_store_dwordx2 v[46:47], v[36:37], off offset:3072
	v_cvt_pk_bf16_f32 v36, v50, v51
	v_cvt_pk_bf16_f32 v37, v52, v53
	global_store_dwordx2 v[46:47], v[36:37], off offset:3584
	s_and_saveexec_b64 s[12:13], s[4:5]
	s_cbranch_execz .LBB0_94
	s_waitcnt lgkmcnt(0)
	v_add_f32_e32 v34, v34, v35
	v_fmamk_f32 v34, v34, 0x3a800000, v115
	v_mul_f32_e32 v35, 0x4b800000, v34
	v_cmp_gt_f32_e32 vcc, s23, v34
	v_mov_b32_e32 v81, v67
	s_nop 0
	v_cndmask_b32_e32 v34, v34, v35, vcc
	v_rsq_f32_e32 v34, v34
	s_nop 0
	v_mul_f32_e32 v35, 0x45800000, v34
	v_cndmask_b32_e32 v36, v34, v35, vcc
	v_lshl_add_u64 v[34:35], v[80:81], 2, s[72:73]
	global_store_dword v[34:35], v36, off offset:8
.LBB0_94:
	s_or_b64 exec, exec, s[12:13]
	s_waitcnt vmcnt(11)
	v_mul_f32_e32 v34, v15, v15
	s_waitcnt vmcnt(10) lgkmcnt(0)
	v_mul_f32_e32 v35, v11, v11
	v_fmac_f32_e32 v34, v14, v14
	v_fmac_f32_e32 v35, v10, v10
	v_fmac_f32_e32 v34, v16, v16
	v_fmac_f32_e32 v35, v12, v12
	v_fmac_f32_e32 v34, v17, v17
	v_fmac_f32_e32 v35, v13, v13
	v_add_f32_e32 v34, v34, v35
	s_waitcnt vmcnt(9)
	v_mul_f32_e32 v35, v7, v7
	v_fmac_f32_e32 v35, v6, v6
	v_fmac_f32_e32 v35, v8, v8
	v_fmac_f32_e32 v35, v9, v9
	v_add_f32_e32 v34, v34, v35
	s_waitcnt vmcnt(8)
	v_mul_f32_e32 v35, v3, v3
	v_fmac_f32_e32 v35, v2, v2
	v_fmac_f32_e32 v35, v4, v4
	v_fmac_f32_e32 v35, v5, v5
	v_add_f32_e32 v34, v34, v35
	v_mov_b32_e32 v35, v34
	v_mov_b32_e32 v127, v34
	s_nop 1
	v_permlane32_swap_b32_e32 v35, v127
	v_lshlrev_b32_e32 v66, 1, v84
	v_cvt_pk_bf16_f32 v30, v30, v31
	v_cvt_pk_bf16_f32 v31, v32, v33
	v_lshl_add_u64 v[32:33], v[74:75], 0, v[66:67]
	s_waitcnt lgkmcnt(0)
	v_add_f32_e32 v34, v35, v127
	v_mov_b32_e32 v35, v34
	v_mov_b32_e32 v127, v34
	s_nop 1
	v_permlane16_swap_b32_e32 v35, v127
	global_store_dwordx2 v[32:33], v[30:31], off
	v_cvt_pk_bf16_f32 v22, v22, v23
	v_cvt_pk_bf16_f32 v23, v24, v25
	global_store_dwordx2 v[32:33], v[22:23], off offset:512
	s_waitcnt lgkmcnt(0)
	v_add_f32_e32 v34, v35, v127
	s_nop 1
	v_mov_b32_dpp v35, v34 row_ror:8 row_mask:0xf bank_mask:0xf
	v_cvt_pk_bf16_f32 v24, v26, v27
	v_cvt_pk_bf16_f32 v25, v28, v29
	v_cvt_pk_bf16_f32 v18, v18, v19
	v_cvt_pk_bf16_f32 v19, v20, v21
	s_waitcnt lgkmcnt(0)
	v_add_f32_e32 v34, v34, v35
	s_nop 1
	v_mov_b32_dpp v35, v34 row_shl:4 row_mask:0xf bank_mask:0x5
	v_mov_b32_dpp v35, v34 row_shr:4 row_mask:0xf bank_mask:0xa
	global_store_dwordx2 v[32:33], v[24:25], off offset:1024
	global_store_dwordx2 v[32:33], v[18:19], off offset:1536
	s_waitcnt lgkmcnt(0)
	v_add_f32_e32 v30, v34, v35
	s_nop 1
	v_mov_b32_dpp v31, v30 quad_perm:[2,3,0,1] row_mask:0xf bank_mask:0xf
	s_waitcnt lgkmcnt(0)
	v_add_f32_e32 v22, v30, v31
	s_nop 1
	v_mov_b32_dpp v23, v22 quad_perm:[1,0,3,2] row_mask:0xf bank_mask:0xf
	s_and_saveexec_b64 s[12:13], s[4:5]
	s_cbranch_execz .LBB0_9
	s_waitcnt lgkmcnt(0)
	v_add_f32_e32 v18, v22, v23
	v_fmamk_f32 v18, v18, 0x3a800000, v115
	v_mul_f32_e32 v19, 0x4b800000, v18
	v_cmp_gt_f32_e32 vcc, s23, v18
	v_mov_b32_e32 v81, v67
	s_nop 0
	v_cndmask_b32_e32 v18, v18, v19, vcc
	v_rsq_f32_e32 v18, v18
	s_nop 0
	v_mul_f32_e32 v19, 0x45800000, v18
	v_cndmask_b32_e32 v20, v18, v19, vcc
	v_lshl_add_u64 v[18:19], v[80:81], 2, s[72:73]
	global_store_dword v[18:19], v20, off offset:12
	s_branch .LBB0_9
